# attention latent loop: single-phase lockstep, softmax VALU in MFMA gaps, speculative exp vs stale max with rebase at tile boundary
# speedup vs baseline: 1.0009x; 1.0009x over previous
.LBB0_130:
	s_or_b64 exec, exec, s[20:21]
	v_add_u32_e32 v4, 0, v4
	v_cmp_lt_i32_e32 vcc, v231, v230
	s_waitcnt vmcnt(0)
	ds_write2_b64 v4, v[0:1], v[2:3] offset1:1
	v_mov_b32_e32 v138, 0
	v_cndmask_b32_e32 v0, v229, v231, vcc
	s_ashr_i32 s5, s4, 31
	s_mov_b32 s35, 0
	v_lshlrev_b32_e32 v135, 2, v0
	v_mov_b32_e32 v147, 0xff800000
	v_mov_b32_e32 v80, v120
	v_mov_b32_e32 v104, v146
	v_mov_b32_e32 v136, v145
	v_mov_b32_e32 v16, 0
	v_mov_b32_e32 v17, v138
	v_mov_b32_e32 v18, v138
	v_mov_b32_e32 v19, v138
	v_mov_b32_e32 v20, v138
	v_mov_b32_e32 v21, v138
	v_mov_b32_e32 v22, v138
	v_mov_b32_e32 v23, v138
	v_mov_b32_e32 v24, v138
	v_mov_b32_e32 v25, v138
	v_mov_b32_e32 v26, v138
	v_mov_b32_e32 v27, v138
	v_mov_b32_e32 v28, v138
	v_mov_b32_e32 v29, v138
	v_mov_b32_e32 v30, v138
	v_mov_b32_e32 v31, v138
	v_mov_b32_e32 v0, 0
	v_mov_b32_e32 v1, v138
	v_mov_b32_e32 v2, v138
	v_mov_b32_e32 v3, v138
	v_mov_b32_e32 v4, v138
	v_mov_b32_e32 v5, v138
	v_mov_b32_e32 v6, v138
	v_mov_b32_e32 v7, v138
	v_mov_b32_e32 v8, v138
	v_mov_b32_e32 v9, v138
	v_mov_b32_e32 v10, v138
	v_mov_b32_e32 v11, v138
	v_mov_b32_e32 v12, v138
	v_mov_b32_e32 v13, v138
	v_mov_b32_e32 v14, v138
	v_mov_b32_e32 v15, v138
	s_waitcnt lgkmcnt(0)
	s_barrier
	v_readfirstlane_b32 s85, v204
	s_mov_b32 s76, 1
	s_movk_i32 s77, 0x3400
	s_movk_i32 s78, 0x2200
	s_movk_i32 s79, 0x4400
	s_mov_b32 s80, 0
	s_movk_i32 s81, 0x3400
	s_movk_i32 s82, 0x6800
	s_mov_b32 s83, 0x8a00
	s_mov_b32 s84, 0xac00
	s_lshr_b32 s85, s85, 8
	s_mov_b32 s35, 0
	s_mov_b32 s87, 0x41000000
	v_mov_b32_e32 v105, v81
	v_mov_b32_e32 v137, v81
	v_lshl_add_u64 v[240:241], v[80:81], 1, s[6:7]
	global_load_dwordx4 v[98:101], v[240:241], off
	v_lshl_add_u64 v[240:241], v[104:105], 1, v[102:103]
	global_load_dwordx4 v[94:97], v[240:241], off
	s_cmp_eq_u32 s85, 0
	s_cbranch_scc0 .Lat_ld1
	v_lshl_add_u64 v[240:241], v[136:137], 1, s[8:9]
	global_load_dwordx4 v[90:93], v[240:241], off
.Lat_ld1:
	v_add_u32_e32 v80, 0x1800, v80
	v_add_u32_e32 v104, v104, v144
	v_add_u32_e32 v136, 64, v136
	ds_read_b128 v[206:209], v142
	ds_read_b128 v[210:213], v142 offset:32
	ds_read_b128 v[214:217], v142 offset:64
	ds_read_b128 v[218:221], v142 offset:96
	ds_read_b128 v[222:225], v142 offset:128
	ds_read_b128 v[164:167], v142 offset:160
	ds_read_b128 v[148:151], v142 offset:6656
	ds_read_b128 v[152:155], v142 offset:6688
	ds_read_b128 v[184:187], v142 offset:6720
	ds_read_b128 v[188:191], v142 offset:6752
	ds_read_b128 v[192:195], v142 offset:6784
	ds_read_b128 v[200:203], v142 offset:6816
	s_waitcnt lgkmcnt(11)
	v_mfma_f32_32x32x16_bf16 v[48:63], v[206:209], v[86:89], 0
	s_waitcnt lgkmcnt(10)
	v_mfma_f32_32x32x16_bf16 v[48:63], v[210:213], v[82:85], v[48:63]
	s_waitcnt lgkmcnt(9)
	v_mfma_f32_32x32x16_bf16 v[48:63], v[214:217], v[76:79], v[48:63]
	s_waitcnt lgkmcnt(8)
	v_mfma_f32_32x32x16_bf16 v[48:63], v[218:221], v[72:75], v[48:63]
	s_waitcnt lgkmcnt(7)
	v_mfma_f32_32x32x16_bf16 v[48:63], v[222:225], v[68:71], v[48:63]
	s_waitcnt lgkmcnt(6)
	v_mfma_f32_32x32x16_bf16 v[48:63], v[164:167], v[64:67], v[48:63]
	s_waitcnt lgkmcnt(5)
	v_mfma_f32_32x32x16_bf16 v[32:47], v[148:151], v[86:89], 0
	s_waitcnt lgkmcnt(4)
	v_mfma_f32_32x32x16_bf16 v[32:47], v[152:155], v[82:85], v[32:47]
	s_waitcnt lgkmcnt(3)
	v_mfma_f32_32x32x16_bf16 v[32:47], v[184:187], v[76:79], v[32:47]
	s_waitcnt lgkmcnt(2)
	v_mfma_f32_32x32x16_bf16 v[32:47], v[188:191], v[72:75], v[32:47]
	s_waitcnt lgkmcnt(1)
	v_mfma_f32_32x32x16_bf16 v[32:47], v[192:195], v[68:71], v[32:47]
	s_waitcnt lgkmcnt(0)
	v_mfma_f32_32x32x16_bf16 v[32:47], v[200:203], v[64:67], v[32:47]
	s_cmpk_gt_u32 s76, 0x47
	s_cbranch_scc1 .Lat_nost2
	s_waitcnt vmcnt(0)
	v_add_u32_e32 v242, s77, v109
	ds_write_b128 v242, v[98:101]
	s_cmp_eq_u32 s85, 0
	s_cbranch_scc0 .Lat_stB3
	v_add_u32_e32 v242, s77, v140
	ds_write_b128 v242, v[94:97]
	v_add_u32_e32 v242, s78, v141
	ds_write2_b64 v242, v[90:91], v[92:93] offset1:1
	s_branch .Lat_std4
.Lat_stB3:
	v_add_u32_e32 v242, s78, v139
	ds_write2_b64 v242, v[94:95], v[96:97] offset1:1
.Lat_std4:
	s_add_i32 s76, s76, 1
	s_xor_b32 s77, s77, 0x3400
	s_mov_b32 s86, s78
	s_mov_b32 s78, s79
	s_mov_b32 s79, s80
	s_mov_b32 s80, s86
	s_cmpk_gt_u32 s76, 0x47
	s_cbranch_scc1 .Lat_nost2
	v_lshl_add_u64 v[240:241], v[80:81], 1, s[6:7]
	global_load_dwordx4 v[98:101], v[240:241], off
	v_lshl_add_u64 v[240:241], v[104:105], 1, v[102:103]
	global_load_dwordx4 v[94:97], v[240:241], off
	s_cmp_eq_u32 s85, 0
	s_cbranch_scc0 .Lat_ld5
	v_lshl_add_u64 v[240:241], v[136:137], 1, s[8:9]
	global_load_dwordx4 v[90:93], v[240:241], off

.Lat_nost2:
	s_nop 7
	s_nop 3
	v_max3_f32 v128, v48, v49, v50
	v_max3_f32 v128, v128, v51, v52
	v_max3_f32 v128, v128, v53, v54
	v_max3_f32 v128, v128, v55, v56
	v_max3_f32 v128, v128, v57, v58
	v_max3_f32 v128, v128, v59, v60
	v_max3_f32 v128, v128, v61, v62
	v_max3_f32 v128, v128, v63, v32
	v_max3_f32 v128, v128, v33, v34
	v_max3_f32 v128, v128, v35, v36
	v_max3_f32 v128, v128, v37, v38
	v_max3_f32 v128, v128, v39, v40
	v_max3_f32 v128, v128, v41, v42
	v_max3_f32 v128, v128, v43, v44
	v_max3_f32 v128, v128, v45, v46
	v_max_f32_e32 v128, v128, v47
	v_mov_b32_e32 v129, v128
	s_nop 1
	v_permlane32_swap_b32_e32 v128, v129
	v_max_f32_e32 v128, v128, v129
	v_sub_f32_e32 v168, 0, v128
	v_sub_f32_e32 v169, 0, v128
	v_sub_f32_e32 v170, 0, v128
	v_sub_f32_e32 v171, 0, v128
	v_sub_f32_e32 v172, 0, v128
	v_sub_f32_e32 v173, 0, v128
	v_sub_f32_e32 v174, 0, v128
	v_sub_f32_e32 v175, 0, v128
	v_sub_f32_e32 v176, 0, v128
	v_sub_f32_e32 v177, 0, v128
	v_sub_f32_e32 v178, 0, v128
	v_sub_f32_e32 v179, 0, v128
	v_sub_f32_e32 v180, 0, v128
	v_sub_f32_e32 v181, 0, v128
	v_sub_f32_e32 v182, 0, v128
	v_sub_f32_e32 v183, 0, v128
	v_sub_f32_e32 v48, v48, v128
	v_sub_f32_e32 v49, v49, v128
	v_sub_f32_e32 v50, v50, v128
	v_sub_f32_e32 v51, v51, v128
	v_sub_f32_e32 v52, v52, v128
	v_sub_f32_e32 v53, v53, v128
	v_sub_f32_e32 v54, v54, v128
	v_sub_f32_e32 v55, v55, v128
	v_sub_f32_e32 v56, v56, v128
	v_sub_f32_e32 v57, v57, v128
	v_sub_f32_e32 v58, v58, v128
	v_sub_f32_e32 v59, v59, v128
	v_sub_f32_e32 v60, v60, v128
	v_sub_f32_e32 v61, v61, v128
	v_sub_f32_e32 v62, v62, v128
	v_sub_f32_e32 v63, v63, v128
	v_sub_f32_e32 v32, v32, v128
	v_sub_f32_e32 v33, v33, v128
	v_sub_f32_e32 v34, v34, v128
	v_sub_f32_e32 v35, v35, v128
	v_sub_f32_e32 v36, v36, v128
	v_sub_f32_e32 v37, v37, v128
	v_sub_f32_e32 v38, v38, v128
	v_sub_f32_e32 v39, v39, v128
	v_sub_f32_e32 v40, v40, v128
	v_sub_f32_e32 v41, v41, v128
	v_sub_f32_e32 v42, v42, v128
	v_sub_f32_e32 v43, v43, v128
	v_sub_f32_e32 v44, v44, v128
	v_sub_f32_e32 v45, v45, v128
	v_sub_f32_e32 v46, v46, v128
	v_sub_f32_e32 v47, v47, v128
	v_exp_f32_e32 v48, v48
	v_exp_f32_e32 v49, v49
	v_exp_f32_e32 v50, v50
	v_exp_f32_e32 v51, v51
	v_exp_f32_e32 v52, v52
	v_exp_f32_e32 v53, v53
	v_exp_f32_e32 v54, v54
	v_exp_f32_e32 v55, v55
	v_exp_f32_e32 v56, v56
	v_exp_f32_e32 v57, v57
	v_exp_f32_e32 v58, v58
	v_exp_f32_e32 v59, v59
	v_exp_f32_e32 v60, v60
	v_exp_f32_e32 v61, v61
	v_exp_f32_e32 v62, v62
	v_exp_f32_e32 v63, v63
	v_cvt_pk_bf16_f32 v148, v48, v49
	v_cvt_pk_bf16_f32 v149, v50, v51
	v_cvt_pk_bf16_f32 v150, v52, v53
	v_cvt_pk_bf16_f32 v151, v54, v55
	v_cvt_pk_bf16_f32 v152, v56, v57
	v_cvt_pk_bf16_f32 v153, v58, v59
	v_cvt_pk_bf16_f32 v154, v60, v61
	v_cvt_pk_bf16_f32 v155, v62, v63
	v_mov_b32_e32 v239, 0xff800000
	v_add_u32_e32 v129, s82, v143
	v_add_u32_e32 v131, 0x1000, v129
	ds_read2_b64 v[184:187], v129 offset1:2
	ds_read2_b64 v[188:191], v131 offset0:32 offset1:34
	ds_read2_b64 v[192:195], v129 offset0:4 offset1:6
	ds_read2_b64 v[200:203], v131 offset0:36 offset1:38
	s_mov_b32 s86, s82
	s_mov_b32 s82, s83
	s_mov_b32 s83, s84
	s_mov_b32 s84, s86
	s_waitcnt lgkmcnt(4)
	s_barrier
.Lat_loop:
	v_add_u32_e32 v130, s81, v142
	ds_read_b128 v[206:209], v130
	ds_read_b128 v[210:213], v130 offset:32
	s_waitcnt lgkmcnt(5)
	v_mfma_f32_32x32x16_bf16 v[16:31], v[184:187], v[148:151], v[16:31]
	ds_read2_b64 v[184:187], v129 offset0:8 offset1:10
	v_add_f32_e32 v226, v48, v49
	v_add_f32_e32 v227, v56, v57
	v_add_f32_e32 v226, v226, v50
	v_add_f32_e32 v227, v227, v58
	v_add_f32_e32 v226, v226, v51
	ds_read_b128 v[214:217], v130 offset:64
	ds_read_b128 v[218:221], v130 offset:96
	s_waitcnt lgkmcnt(7)
	v_mfma_f32_32x32x16_bf16 v[0:15], v[188:191], v[148:151], v[0:15]
	ds_read2_b64 v[188:191], v131 offset0:40 offset1:42
	v_add_f32_e32 v227, v227, v59
	v_add_f32_e32 v226, v226, v52
	v_add_f32_e32 v227, v227, v60
	v_add_f32_e32 v226, v226, v53
	v_add_f32_e32 v227, v227, v61
	v_add_f32_e32 v226, v226, v54
	ds_read_b128 v[222:225], v130 offset:128
	ds_read_b128 v[164:167], v130 offset:160
	s_waitcnt lgkmcnt(9)
	v_mfma_f32_32x32x16_bf16 v[16:31], v[192:195], v[152:155], v[16:31]
	ds_read2_b64 v[192:195], v129 offset0:12 offset1:14
	v_add_f32_e32 v227, v227, v62
	v_add_f32_e32 v226, v226, v55
	v_add_f32_e32 v227, v227, v63
	v_max3_f32 v128, v239, v32, v33
	v_max3_f32 v128, v128, v34, v35
	s_waitcnt lgkmcnt(9)
	v_mfma_f32_32x32x16_bf16 v[0:15], v[200:203], v[152:155], v[0:15]
	ds_read2_b64 v[200:203], v131 offset0:44 offset1:46
	v_max3_f32 v128, v128, v36, v37
	v_max3_f32 v128, v128, v38, v39
	v_max3_f32 v128, v128, v40, v41
	v_max3_f32 v128, v128, v42, v43
	v_max3_f32 v128, v128, v44, v45
	v_max3_f32 v128, v128, v46, v47
	s_waitcnt lgkmcnt(2)
	v_mfma_f32_32x32x16_bf16 v[48:63], v[206:209], v[86:89], v[168:183]
	ds_read_b128 v[206:209], v130 offset:6656
	v_exp_f32_e32 v32, v32
	v_exp_f32_e32 v33, v33
	v_exp_f32_e32 v34, v34
	v_mfma_f32_32x32x16_bf16 v[48:63], v[210:213], v[82:85], v[48:63]
	ds_read_b128 v[210:213], v130 offset:6688
	v_exp_f32_e32 v35, v35
	v_exp_f32_e32 v36, v36
	v_exp_f32_e32 v37, v37
	v_exp_f32_e32 v38, v38
	v_mfma_f32_32x32x16_bf16 v[48:63], v[214:217], v[76:79], v[48:63]
	ds_read_b128 v[214:217], v130 offset:6720
	v_exp_f32_e32 v39, v39
	v_exp_f32_e32 v40, v40
	v_exp_f32_e32 v41, v41
	v_mov_b32_e32 v242, v128
	v_mfma_f32_32x32x16_bf16 v[48:63], v[218:221], v[72:75], v[48:63]
	ds_read_b128 v[218:221], v130 offset:6752
	s_nop 1
	v_permlane32_swap_b32_e32 v128, v242
	v_max_f32_e32 v128, v128, v242
	v_mfma_f32_32x32x16_bf16 v[48:63], v[222:225], v[68:71], v[48:63]
	ds_read_b128 v[222:225], v130 offset:6784
	v_cmp_lt_f32_e32 vcc, s87, v128
	s_mov_b64 s[88:89], vcc
	v_exp_f32_e32 v42, v42
	v_exp_f32_e32 v43, v43
	v_mfma_f32_32x32x16_bf16 v[48:63], v[164:167], v[64:67], v[48:63]
	ds_read_b128 v[164:167], v130 offset:6816
	v_exp_f32_e32 v44, v44
	v_exp_f32_e32 v45, v45
	v_exp_f32_e32 v46, v46
	v_exp_f32_e32 v47, v47
	v_cvt_pk_bf16_f32 v156, v32, v33
	v_cvt_pk_bf16_f32 v157, v34, v35
	v_cvt_pk_bf16_f32 v158, v36, v37
	v_cvt_pk_bf16_f32 v159, v38, v39
	v_cvt_pk_bf16_f32 v160, v40, v41
	v_cvt_pk_bf16_f32 v161, v42, v43
	v_cvt_pk_bf16_f32 v162, v44, v45
	v_cvt_pk_bf16_f32 v163, v46, v47
	v_mfma_f32_32x32x16_bf16 v[16:31], v[184:187], v[156:159], v[16:31]
	v_add_f32_e32 v248, v32, v33
	v_add_f32_e32 v249, v40, v41
	v_add_f32_e32 v248, v248, v34
	v_add_f32_e32 v249, v249, v42
	v_mfma_f32_32x32x16_bf16 v[0:15], v[188:191], v[156:159], v[0:15]
	v_add_f32_e32 v248, v248, v35
	v_add_f32_e32 v249, v249, v43
	v_add_f32_e32 v248, v248, v36
	v_add_f32_e32 v249, v249, v44
	v_add_f32_e32 v248, v248, v37
	s_waitcnt lgkmcnt(7)
	v_mfma_f32_32x32x16_bf16 v[16:31], v[192:195], v[160:163], v[16:31]
	v_add_f32_e32 v249, v249, v45
	v_add_f32_e32 v248, v248, v38
	v_add_f32_e32 v249, v249, v46
	v_add_f32_e32 v248, v248, v39
	s_waitcnt lgkmcnt(6)
	v_mfma_f32_32x32x16_bf16 v[0:15], v[200:203], v[160:163], v[0:15]
	v_add_f32_e32 v249, v249, v47
	v_add_f32_e32 v226, v226, v227
	v_add_f32_e32 v248, v248, v249
	v_add_f32_e32 v226, v226, v248
	v_add_f32_e32 v138, v138, v226
	s_waitcnt lgkmcnt(0)
	v_mfma_f32_32x32x16_bf16 v[32:47], v[206:209], v[86:89], v[168:183]
	v_max3_f32 v239, v48, v49, v50
	v_max3_f32 v239, v239, v51, v52
	v_max3_f32 v239, v239, v53, v54
	v_max3_f32 v239, v239, v55, v56
	v_max3_f32 v239, v239, v57, v58
	v_max3_f32 v239, v239, v59, v60
	v_mfma_f32_32x32x16_bf16 v[32:47], v[210:213], v[82:85], v[32:47]
	v_max3_f32 v239, v239, v61, v62
	v_max_f32_e32 v239, v239, v63
	v_exp_f32_e32 v48, v48
	v_exp_f32_e32 v49, v49
	v_mfma_f32_32x32x16_bf16 v[32:47], v[214:217], v[76:79], v[32:47]
	v_exp_f32_e32 v50, v50
	v_exp_f32_e32 v51, v51
	v_exp_f32_e32 v52, v52
	v_mfma_f32_32x32x16_bf16 v[32:47], v[218:221], v[72:75], v[32:47]
	v_exp_f32_e32 v53, v53
	v_exp_f32_e32 v54, v54
	v_exp_f32_e32 v55, v55
	v_mfma_f32_32x32x16_bf16 v[32:47], v[222:225], v[68:71], v[32:47]
	v_exp_f32_e32 v56, v56
	v_exp_f32_e32 v57, v57
	v_exp_f32_e32 v58, v58
	v_mfma_f32_32x32x16_bf16 v[32:47], v[164:167], v[64:67], v[32:47]
	v_exp_f32_e32 v59, v59
	v_exp_f32_e32 v60, v60
	v_exp_f32_e32 v61, v61
	v_exp_f32_e32 v62, v62
	v_exp_f32_e32 v63, v63
	v_cvt_pk_bf16_f32 v148, v48, v49
	v_cvt_pk_bf16_f32 v149, v50, v51
	v_cvt_pk_bf16_f32 v150, v52, v53
	v_cvt_pk_bf16_f32 v151, v54, v55
	v_cvt_pk_bf16_f32 v152, v56, v57
	v_cvt_pk_bf16_f32 v153, v58, v59
	v_cvt_pk_bf16_f32 v154, v60, v61
	v_cvt_pk_bf16_f32 v155, v62, v63
	s_cmpk_gt_u32 s76, 0x47
	s_cbranch_scc1 .Lat_nost6
	s_waitcnt vmcnt(0)
	v_add_u32_e32 v242, s77, v109
	ds_write_b128 v242, v[98:101]
	s_cmp_eq_u32 s85, 0
	s_cbranch_scc0 .Lat_stB7
	v_add_u32_e32 v242, s77, v140
	ds_write_b128 v242, v[94:97]
	v_add_u32_e32 v242, s78, v141
	ds_write2_b64 v242, v[90:91], v[92:93] offset1:1
	s_branch .Lat_std8

.Lat_nost6:
	v_add_u32_e32 v129, s82, v143
	v_add_u32_e32 v131, 0x1000, v129
	ds_read2_b64 v[184:187], v129 offset1:2
	ds_read2_b64 v[188:191], v131 offset0:32 offset1:34
	ds_read2_b64 v[192:195], v129 offset0:4 offset1:6
	ds_read2_b64 v[200:203], v131 offset0:36 offset1:38
	s_mov_b32 s86, s82
	s_mov_b32 s82, s83
	s_mov_b32 s83, s84
	s_mov_b32 s84, s86
	s_xor_b32 s81, s81, 0x3400
	s_add_i32 s35, s35, 1
	s_cmp_lg_u64 s[88:89], 0
	s_cbranch_scc1 .Lat_resc
.Lat_resc_back:
	s_cmpk_lt_u32 s35, 0x47
	s_waitcnt lgkmcnt(4)
	s_barrier
	s_cbranch_scc1 .Lat_loop
	s_waitcnt lgkmcnt(0)
	s_nop 7
	s_nop 7
	v_sub_f32_e32 v105, 0, v168
	v_mov_b32_e32 v98, v138
	s_branch .LBB0_105
.Lat_resc:
	s_nop 7
	s_nop 7
	v_max_f32_e32 v242, 0, v128
	v_exp_f32_e64 v243, -v242
	v_sub_f32_e32 v32, v32, v242
	v_sub_f32_e32 v33, v33, v242
	v_sub_f32_e32 v34, v34, v242
	v_sub_f32_e32 v35, v35, v242
	v_sub_f32_e32 v36, v36, v242
	v_sub_f32_e32 v37, v37, v242
	v_sub_f32_e32 v38, v38, v242
	v_sub_f32_e32 v39, v39, v242
	v_sub_f32_e32 v40, v40, v242
	v_sub_f32_e32 v41, v41, v242
	v_sub_f32_e32 v42, v42, v242
	v_sub_f32_e32 v43, v43, v242
	v_sub_f32_e32 v44, v44, v242
	v_sub_f32_e32 v45, v45, v242
	v_sub_f32_e32 v46, v46, v242
	v_sub_f32_e32 v47, v47, v242
	v_sub_f32_e32 v168, v168, v242
	v_sub_f32_e32 v169, v169, v242
	v_sub_f32_e32 v170, v170, v242
	v_sub_f32_e32 v171, v171, v242
	v_sub_f32_e32 v172, v172, v242
	v_sub_f32_e32 v173, v173, v242
	v_sub_f32_e32 v174, v174, v242
	v_sub_f32_e32 v175, v175, v242
	v_sub_f32_e32 v176, v176, v242
	v_sub_f32_e32 v177, v177, v242
	v_sub_f32_e32 v178, v178, v242
	v_sub_f32_e32 v179, v179, v242
	v_sub_f32_e32 v180, v180, v242
	v_sub_f32_e32 v181, v181, v242
	v_sub_f32_e32 v182, v182, v242
	v_sub_f32_e32 v183, v183, v242
	v_sub_f32_e32 v239, v239, v242
	v_mul_f32_e32 v48, v48, v243
	v_mul_f32_e32 v49, v49, v243
	v_mul_f32_e32 v50, v50, v243
	v_mul_f32_e32 v51, v51, v243
	v_mul_f32_e32 v52, v52, v243
	v_mul_f32_e32 v53, v53, v243
	v_mul_f32_e32 v54, v54, v243
	v_mul_f32_e32 v55, v55, v243
	v_mul_f32_e32 v56, v56, v243
	v_mul_f32_e32 v57, v57, v243
	v_mul_f32_e32 v58, v58, v243
	v_mul_f32_e32 v59, v59, v243
	v_mul_f32_e32 v60, v60, v243
	v_mul_f32_e32 v61, v61, v243
	v_mul_f32_e32 v62, v62, v243
	v_mul_f32_e32 v63, v63, v243
	v_mul_f32_e32 v0, v0, v243
	v_mul_f32_e32 v1, v1, v243
	v_mul_f32_e32 v2, v2, v243
	v_mul_f32_e32 v3, v3, v243
	v_mul_f32_e32 v4, v4, v243
	v_mul_f32_e32 v5, v5, v243
	v_mul_f32_e32 v6, v6, v243
	v_mul_f32_e32 v7, v7, v243
	v_mul_f32_e32 v8, v8, v243
	v_mul_f32_e32 v9, v9, v243
	v_mul_f32_e32 v10, v10, v243
	v_mul_f32_e32 v11, v11, v243
	v_mul_f32_e32 v12, v12, v243
	v_mul_f32_e32 v13, v13, v243
	v_mul_f32_e32 v14, v14, v243
	v_mul_f32_e32 v15, v15, v243
	v_mul_f32_e32 v16, v16, v243
	v_mul_f32_e32 v17, v17, v243
	v_mul_f32_e32 v18, v18, v243
	v_mul_f32_e32 v19, v19, v243
	v_mul_f32_e32 v20, v20, v243
	v_mul_f32_e32 v21, v21, v243
	v_mul_f32_e32 v22, v22, v243
	v_mul_f32_e32 v23, v23, v243
	v_mul_f32_e32 v24, v24, v243
	v_mul_f32_e32 v25, v25, v243
	v_mul_f32_e32 v26, v26, v243
	v_mul_f32_e32 v27, v27, v243
	v_mul_f32_e32 v28, v28, v243
	v_mul_f32_e32 v29, v29, v243
	v_mul_f32_e32 v30, v30, v243
	v_mul_f32_e32 v31, v31, v243
	v_mul_f32_e32 v138, v138, v243
	v_cvt_pk_bf16_f32 v148, v48, v49
	v_cvt_pk_bf16_f32 v149, v50, v51
	v_cvt_pk_bf16_f32 v150, v52, v53
	v_cvt_pk_bf16_f32 v151, v54, v55
	v_cvt_pk_bf16_f32 v152, v56, v57
	v_cvt_pk_bf16_f32 v153, v58, v59
	v_cvt_pk_bf16_f32 v154, v60, v61
	v_cvt_pk_bf16_f32 v155, v62, v63
	s_branch .Lat_resc_back
